# attention combine pass L0: 16 O1/O2 loads of a unit hoisted to the top of the output loop, counted waits
# baseline (speedup 1.0000x reference)
; #define GAS __attribute__((address_space(1)))
; #define LAS __attribute__((address_space(3)))
; __device__ __forceinline__ void unpack8(const v4u w, float (&f)[8]) { f[0] = bfl(w.x); f[1] = bfh(w.x); f[2] = bfl(w.y); f[3] = bfh(w.y); f[4] = bfl(w.z); f[5] = bfh(w.z); f[6] = bfl(w.w); f[7] = bfh(w.w); }
; __device__ __forceinline__ v4u pack8(const float (&f)[8]) { v4u w; w.x = pk2(f[0], f[1]); w.y = pk2(f[2], f[3]); w.z = pk2(f[4], f[5]); w.w = pk2(f[6], f[7]); return w; }
; template <bool COMBINE>
; __device__ __forceinline__ void attn_phase(Frame& F, const bf16* QKV, bf16* O12, float* LSE, bf16* MO) {
;     ...
;         for (int i = 0; i < 8; ++i) { const int ci = i * 64 + lane, row = ci >> 4, ch = ci & 15;
;             const v4u t = *(const LAS v4u*)(stg + row * SROW + ch * 16);
;             const size_t go = (size_t)tokrow(b, qw0 + row, Lsh) * D + h * 128 + ch * 8;
;             if (!COMBINE) *(GAS v4u*)(O12 + (size_t)(gg - 1) * M * D + go) = t;
;             else { const f32x4 wt = *(const LAS f32x4*)(stg + 32 * SROW + row * 16);
;                 const v4u a = *(const GAS v4u*)(O12 + go), bq = *(const GAS v4u*)(O12 + (size_t)M * D + go);
;                 float f0[8], f1[8], f2[8], r[8]; unpack8(t, f0); unpack8(a, f1); unpack8(bq, f2);
; #pragma unroll
;                 for (int jj = 0; jj < 8; ++jj) r[jj] = wt[0] * f0[jj] + wt[1] * f1[jj] + wt[2] * f2[jj];
;                 *(GAS v4u*)(MO + go) = pack8(r); }
.LBB0_411:
	s_or_b64 exec, exec, s[4:5]
	v_ashrrev_i32_e32 v10, 4, v198
	v_add_u32_e32 v0, s54, v10
	v_and_b32_e32 v1, 0x7ff, v0
	v_ashrrev_i32_e32 v0, 11, v0
	v_add3_u32 v0, v0, s35, v1
	v_ashrrev_i32_e32 v1, 31, v0
	v_lshlrev_b64 v[18:19], 12, v[0:1]
	v_lshl_or_b32 v1, s6, 1, v188
	v_or_b32_e32 v18, v18, v1
	s_waitcnt lgkmcnt(0)
	v_lshl_add_u64 v[6:7], s[0:1], 0, v[18:19]
	v_lshl_add_u64 v[2:3], s[64:65], 0, v[18:19]
	global_load_dwordx4 v[64:67], v18, s[64:65]
	global_load_dwordx4 v[68:71], v18, s[0:1]
	s_add_u32 vcc_lo, s64, 0x4000
	s_addc_u32 vcc_hi, s65, 0
	global_load_dwordx4 v[72:75], v18, vcc
	s_add_u32 s4, s0, 0x4000
	s_addc_u32 s5, s1, 0
	global_load_dwordx4 v[76:79], v18, s[4:5]
	s_add_u32 vcc_lo, s64, 0x8000
	s_addc_u32 vcc_hi, s65, 0
	global_load_dwordx4 v[80:83], v18, vcc
	s_add_u32 s4, s0, 0x8000
	s_addc_u32 s5, s1, 0
	global_load_dwordx4 v[84:87], v18, s[4:5]
	s_add_u32 vcc_lo, s64, 0xc000
	s_addc_u32 vcc_hi, s65, 0
	global_load_dwordx4 v[88:91], v18, vcc
	s_add_u32 s4, s0, 0xc000
	s_addc_u32 s5, s1, 0
	global_load_dwordx4 v[92:95], v18, s[4:5]
	s_add_u32 vcc_lo, s64, 0x10000
	s_addc_u32 vcc_hi, s65, 0
	global_load_dwordx4 v[96:99], v18, vcc
	s_add_u32 s4, s0, 0x10000
	s_addc_u32 s5, s1, 0
	global_load_dwordx4 v[100:103], v18, s[4:5]
	s_add_u32 vcc_lo, s64, 0x14000
	s_addc_u32 vcc_hi, s65, 0
	global_load_dwordx4 v[104:107], v18, vcc
	s_add_u32 s4, s0, 0x14000
	s_addc_u32 s5, s1, 0
	global_load_dwordx4 v[108:111], v18, s[4:5]
	s_add_u32 vcc_lo, s64, 0x18000
	s_addc_u32 vcc_hi, s65, 0
	global_load_dwordx4 v[112:115], v18, vcc
	s_add_u32 s4, s0, 0x18000
	s_addc_u32 s5, s1, 0
	global_load_dwordx4 v[116:119], v18, s[4:5]
	s_add_u32 vcc_lo, s64, 0x1c000
	s_addc_u32 vcc_hi, s65, 0
	global_load_dwordx4 v[120:123], v18, vcc
	s_add_u32 s4, s0, 0x1c000
	s_addc_u32 s5, s1, 0
	global_load_dwordx4 v[124:127], v18, s[4:5]
	v_add_u32_e32 v0, s77, v188
	v_and_b32_e32 v12, -16, v198
	v_mad_u64_u32 v[10:11], s[4:5], v10, s59, v[0:1]
	v_add_u32_e32 v14, s77, v12
	ds_read_b128 v[10:13], v10
	ds_read_b128 v[14:17], v14 offset:8704
	v_add_u32_e32 v32, 64, v198
	v_ashrrev_i32_e32 v33, 4, v32
	s_waitcnt lgkmcnt(0)
	v_add_u32_e32 v17, s54, v33
	v_and_b32_e32 v20, 0x7ff, v17
	v_ashrrev_i32_e32 v17, 11, v17
	v_add3_u32 v20, v17, s35, v20
	v_lshlrev_b32_e32 v34, 16, v10
	v_and_b32_e32 v35, 0xffff0000, v10
	v_lshlrev_b32_e32 v36, 16, v11
	v_and_b32_e32 v37, 0xffff0000, v11
	v_mov_b32_e32 v10, v15
	v_mov_b32_e32 v11, v16
	v_ashrrev_i32_e32 v21, 31, v20
	v_and_b32_e32 v41, 0xffff0000, v13
	v_lshlrev_b64 v[20:21], 12, v[20:21]
	v_lshlrev_b32_e32 v38, 16, v12
	v_and_b32_e32 v39, 0xffff0000, v12
	v_lshlrev_b32_e32 v40, 16, v13
	v_lshl_add_u64 v[12:13], s[62:63], 0, v[18:19]
	v_or_b32_e32 v20, v20, v1
	v_lshl_add_u64 v[18:19], s[64:65], 0, v[20:21]
	v_lshl_add_u64 v[16:17], s[0:1], 0, v[20:21]
	s_add_i32 s34, s34, s52
	s_add_i32 s78, s78, s79
	s_add_i32 s80, s80, s81
	s_cmpk_lt_i32 s34, 0x200
	s_waitcnt vmcnt(14)
	v_mov_b32_e32 v2, v64
	v_mov_b32_e32 v3, v65
	v_mov_b32_e32 v4, v66
	v_mov_b32_e32 v5, v67
	v_mov_b32_e32 v6, v68
	v_mov_b32_e32 v7, v69
	v_mov_b32_e32 v8, v70
	v_mov_b32_e32 v9, v71
	v_lshlrev_b32_e32 v23, 16, v2
	v_and_b32_e32 v25, 0xffff0000, v2
	v_lshlrev_b32_e32 v27, 16, v3
	v_lshlrev_b32_e32 v26, 16, v7
	v_and_b32_e32 v3, 0xffff0000, v3
	v_and_b32_e32 v2, 0xffff0000, v7
	v_lshlrev_b32_e32 v7, 16, v4
	v_and_b32_e32 v29, 0xffff0000, v4
	v_lshlrev_b32_e32 v31, 16, v5
	v_and_b32_e32 v5, 0xffff0000, v5
	v_and_b32_e32 v4, 0xffff0000, v9
	v_lshlrev_b32_e32 v22, 16, v6
	v_and_b32_e32 v24, 0xffff0000, v6
	v_lshlrev_b32_e32 v6, 16, v8
	v_and_b32_e32 v28, 0xffff0000, v8
	v_lshlrev_b32_e32 v30, 16, v9
	v_pk_mul_f32 v[2:3], v[10:11], v[2:3]
	v_pk_mul_f32 v[4:5], v[10:11], v[4:5]
	v_pk_mul_f32 v[8:9], v[10:11], v[22:23]
	v_pk_mul_f32 v[22:23], v[10:11], v[24:25]
	v_pk_mul_f32 v[24:25], v[10:11], v[26:27]
	v_pk_mul_f32 v[6:7], v[10:11], v[6:7]
	v_pk_mul_f32 v[26:27], v[10:11], v[28:29]
	v_pk_mul_f32 v[28:29], v[10:11], v[30:31]
	v_fma_f32 v2, v14, v37, v2
	v_fma_f32 v4, v14, v41, v4
	v_fma_f32 v8, v14, v34, v8
	v_fma_f32 v10, v14, v35, v22
	v_fma_f32 v11, v14, v36, v24
	v_fma_f32 v6, v14, v38, v6
	v_fma_f32 v15, v14, v39, v26
	v_fma_f32 v22, v14, v40, v28
	v_add_f32_e32 v3, v2, v3
	v_add_f32_e32 v5, v4, v5
	v_add_f32_e32 v8, v8, v9
	v_add_f32_e32 v9, v10, v23
	v_add_f32_e32 v10, v11, v25
	v_add_f32_e32 v6, v6, v7
	v_add_f32_e32 v7, v15, v27
	v_add_f32_e32 v11, v22, v29
	v_cvt_pk_bf16_f32 v2, v8, v9
	v_cvt_pk_bf16_f32 v3, v10, v3
	v_cvt_pk_bf16_f32 v4, v6, v7
	v_cvt_pk_bf16_f32 v5, v11, v5
	global_store_dwordx4 v[12:13], v[2:5], off
	v_and_b32_e32 v12, -16, v32
	v_mad_u64_u32 v[10:11], s[4:5], v33, s59, v[0:1]
	v_add_u32_e32 v14, s77, v12
	ds_read_b128 v[10:13], v10
	ds_read_b128 v[14:17], v14 offset:8704
	v_add_u32_e32 v34, 0x80, v198
	v_ashrrev_i32_e32 v32, 4, v34
	v_add_u32_e32 v18, s54, v32
	s_waitcnt lgkmcnt(0)
	v_and_b32_e32 v17, 0x7ff, v18
	v_ashrrev_i32_e32 v18, 11, v18
	v_add3_u32 v18, v18, s35, v17
	v_lshlrev_b32_e32 v33, 16, v10
	v_and_b32_e32 v35, 0xffff0000, v10
	v_lshlrev_b32_e32 v36, 16, v11
	v_and_b32_e32 v37, 0xffff0000, v11
	v_mov_b32_e32 v10, v15
	v_mov_b32_e32 v11, v16
	v_ashrrev_i32_e32 v19, 31, v18
	v_and_b32_e32 v41, 0xffff0000, v13
	v_lshlrev_b64 v[18:19], 12, v[18:19]
	v_lshlrev_b32_e32 v38, 16, v12
	v_and_b32_e32 v39, 0xffff0000, v12
	v_lshlrev_b32_e32 v40, 16, v13
	v_or_b32_e32 v18, v18, v1
	v_lshl_add_u64 v[12:13], s[62:63], 0, v[20:21]
	v_lshl_add_u64 v[20:21], s[64:65], 0, v[18:19]
	v_lshl_add_u64 v[16:17], s[0:1], 0, v[18:19]
	s_waitcnt vmcnt(13)
; #define GAS __attribute__((address_space(1)))
; #define LAS __attribute__((address_space(3)))
; __device__ __forceinline__ void unpack8(const v4u w, float (&f)[8]) { f[0] = bfl(w.x); f[1] = bfh(w.x); f[2] = bfl(w.y); f[3] = bfh(w.y); f[4] = bfl(w.z); f[5] = bfh(w.z); f[6] = bfl(w.w); f[7] = bfh(w.w); }
; __device__ __forceinline__ v4u pack8(const float (&f)[8]) { v4u w; w.x = pk2(f[0], f[1]); w.y = pk2(f[2], f[3]); w.z = pk2(f[4], f[5]); w.w = pk2(f[6], f[7]); return w; }
; template <bool COMBINE>
; __device__ __forceinline__ void attn_phase(Frame& F, const bf16* QKV, bf16* O12, float* LSE, bf16* MO) {
;     ...
;         for (int i = 0; i < 8; ++i) { const int ci = i * 64 + lane, row = ci >> 4, ch = ci & 15;
;             const v4u t = *(const LAS v4u*)(stg + row * SROW + ch * 16);
;             const size_t go = (size_t)tokrow(b, qw0 + row, Lsh) * D + h * 128 + ch * 8;
;             if (!COMBINE) *(GAS v4u*)(O12 + (size_t)(gg - 1) * M * D + go) = t;
;             else { const f32x4 wt = *(const LAS f32x4*)(stg + 32 * SROW + row * 16);
;                 const v4u a = *(const GAS v4u*)(O12 + go), bq = *(const GAS v4u*)(O12 + (size_t)M * D + go);
;                 float f0[8], f1[8], f2[8], r[8]; unpack8(t, f0); unpack8(a, f1); unpack8(bq, f2);
; #pragma unroll
;                 for (int jj = 0; jj < 8; ++jj) r[jj] = wt[0] * f0[jj] + wt[1] * f1[jj] + wt[2] * f2[jj];
;                 *(GAS v4u*)(MO + go) = pack8(r); }
	v_mov_b32_e32 v2, v72
	v_mov_b32_e32 v3, v73
	v_mov_b32_e32 v4, v74
	v_mov_b32_e32 v5, v75
	v_mov_b32_e32 v6, v76
	v_mov_b32_e32 v7, v77
	v_mov_b32_e32 v8, v78
	v_mov_b32_e32 v9, v79
	v_lshlrev_b32_e32 v23, 16, v2
	v_and_b32_e32 v25, 0xffff0000, v2
	v_lshlrev_b32_e32 v27, 16, v3
	v_lshlrev_b32_e32 v26, 16, v7
	v_and_b32_e32 v3, 0xffff0000, v3
	v_and_b32_e32 v2, 0xffff0000, v7
	v_lshlrev_b32_e32 v7, 16, v4
	v_and_b32_e32 v29, 0xffff0000, v4
	v_lshlrev_b32_e32 v31, 16, v5
	v_and_b32_e32 v5, 0xffff0000, v5
	v_and_b32_e32 v4, 0xffff0000, v9
	v_lshlrev_b32_e32 v22, 16, v6
	v_and_b32_e32 v24, 0xffff0000, v6
	v_lshlrev_b32_e32 v6, 16, v8
	v_and_b32_e32 v28, 0xffff0000, v8
	v_lshlrev_b32_e32 v30, 16, v9
	v_pk_mul_f32 v[2:3], v[10:11], v[2:3]
	v_pk_mul_f32 v[4:5], v[10:11], v[4:5]
	v_pk_mul_f32 v[8:9], v[10:11], v[22:23]
	v_pk_mul_f32 v[22:23], v[10:11], v[24:25]
	v_pk_mul_f32 v[24:25], v[10:11], v[26:27]
	v_pk_mul_f32 v[6:7], v[10:11], v[6:7]
	v_pk_mul_f32 v[26:27], v[10:11], v[28:29]
	v_pk_mul_f32 v[28:29], v[10:11], v[30:31]
	v_fma_f32 v2, v14, v37, v2
	v_fma_f32 v4, v14, v41, v4
	v_fma_f32 v8, v14, v33, v8
	v_fma_f32 v10, v14, v35, v22
	v_fma_f32 v11, v14, v36, v24
	v_fma_f32 v6, v14, v38, v6
	v_fma_f32 v15, v14, v39, v26
	v_fma_f32 v22, v14, v40, v28
	v_add_f32_e32 v3, v2, v3
	v_add_f32_e32 v5, v4, v5
	v_add_f32_e32 v8, v8, v9
	v_add_f32_e32 v9, v10, v23
	v_add_f32_e32 v10, v11, v25
	v_add_f32_e32 v6, v6, v7
	v_add_f32_e32 v7, v15, v27
	v_add_f32_e32 v11, v22, v29
	v_cvt_pk_bf16_f32 v2, v8, v9
	v_cvt_pk_bf16_f32 v3, v10, v3
	v_cvt_pk_bf16_f32 v4, v6, v7
	v_cvt_pk_bf16_f32 v5, v11, v5
	global_store_dwordx4 v[12:13], v[2:5], off
	v_and_b32_e32 v12, -16, v34
	v_mad_u64_u32 v[10:11], s[4:5], v32, s59, v[0:1]
	v_add_u32_e32 v14, s77, v12
	ds_read_b128 v[10:13], v10
	ds_read_b128 v[14:17], v14 offset:8704
	v_add_u32_e32 v33, 0xc0, v198
	v_ashrrev_i32_e32 v34, 4, v33
	v_add_u32_e32 v20, s54, v34
	s_waitcnt lgkmcnt(0)
	v_and_b32_e32 v17, 0x7ff, v20
	v_ashrrev_i32_e32 v20, 11, v20
	v_add3_u32 v20, v20, s35, v17
	v_lshlrev_b32_e32 v32, 16, v10
	v_and_b32_e32 v35, 0xffff0000, v10
	v_lshlrev_b32_e32 v36, 16, v11
	v_and_b32_e32 v37, 0xffff0000, v11
	v_mov_b32_e32 v10, v15
	v_mov_b32_e32 v11, v16
	v_ashrrev_i32_e32 v21, 31, v20
	v_and_b32_e32 v41, 0xffff0000, v13
	v_lshlrev_b64 v[20:21], 12, v[20:21]
	v_lshlrev_b32_e32 v38, 16, v12
	v_and_b32_e32 v39, 0xffff0000, v12
	v_lshlrev_b32_e32 v40, 16, v13
	v_or_b32_e32 v20, v20, v1
	v_lshl_add_u64 v[12:13], s[62:63], 0, v[18:19]
	v_lshl_add_u64 v[18:19], s[64:65], 0, v[20:21]
	v_lshl_add_u64 v[16:17], s[0:1], 0, v[20:21]
	s_waitcnt vmcnt(12)
	v_mov_b32_e32 v2, v80
	v_mov_b32_e32 v3, v81
	v_mov_b32_e32 v4, v82
	v_mov_b32_e32 v5, v83
	v_mov_b32_e32 v6, v84
	v_mov_b32_e32 v7, v85
	v_mov_b32_e32 v8, v86
	v_mov_b32_e32 v9, v87
	v_lshlrev_b32_e32 v23, 16, v2
	v_and_b32_e32 v25, 0xffff0000, v2
	v_lshlrev_b32_e32 v27, 16, v3
	v_lshlrev_b32_e32 v26, 16, v7
	v_and_b32_e32 v3, 0xffff0000, v3
	v_and_b32_e32 v2, 0xffff0000, v7
	v_lshlrev_b32_e32 v7, 16, v4
	v_and_b32_e32 v29, 0xffff0000, v4
	v_lshlrev_b32_e32 v31, 16, v5
	v_and_b32_e32 v5, 0xffff0000, v5
	v_and_b32_e32 v4, 0xffff0000, v9
	v_lshlrev_b32_e32 v22, 16, v6
	v_and_b32_e32 v24, 0xffff0000, v6
	v_lshlrev_b32_e32 v6, 16, v8
	v_and_b32_e32 v28, 0xffff0000, v8
	v_lshlrev_b32_e32 v30, 16, v9
	v_pk_mul_f32 v[2:3], v[10:11], v[2:3]
	v_pk_mul_f32 v[4:5], v[10:11], v[4:5]
	v_pk_mul_f32 v[8:9], v[10:11], v[22:23]
	v_pk_mul_f32 v[22:23], v[10:11], v[24:25]
	v_pk_mul_f32 v[24:25], v[10:11], v[26:27]
	v_pk_mul_f32 v[6:7], v[10:11], v[6:7]
	v_pk_mul_f32 v[26:27], v[10:11], v[28:29]
	v_pk_mul_f32 v[28:29], v[10:11], v[30:31]
	v_fma_f32 v2, v14, v37, v2
	v_fma_f32 v4, v14, v41, v4
	v_fma_f32 v8, v14, v32, v8
	v_fma_f32 v10, v14, v35, v22
	v_fma_f32 v11, v14, v36, v24
	v_fma_f32 v6, v14, v38, v6
	v_fma_f32 v15, v14, v39, v26
	v_fma_f32 v22, v14, v40, v28
	v_add_f32_e32 v3, v2, v3
	v_add_f32_e32 v5, v4, v5
	v_add_f32_e32 v8, v8, v9
	v_add_f32_e32 v9, v10, v23
	v_add_f32_e32 v10, v11, v25
	v_add_f32_e32 v6, v6, v7
	v_add_f32_e32 v7, v15, v27
	v_add_f32_e32 v11, v22, v29
	v_cvt_pk_bf16_f32 v2, v8, v9
	v_cvt_pk_bf16_f32 v3, v10, v3
	v_cvt_pk_bf16_f32 v4, v6, v7
	v_cvt_pk_bf16_f32 v5, v11, v5
	global_store_dwordx4 v[12:13], v[2:5], off
	v_and_b32_e32 v12, -16, v33
	v_mad_u64_u32 v[10:11], s[4:5], v34, s59, v[0:1]
	v_add_u32_e32 v14, s77, v12
	ds_read_b128 v[10:13], v10
	ds_read_b128 v[14:17], v14 offset:8704
	v_add_u32_e32 v32, 0x100, v198
	v_ashrrev_i32_e32 v33, 4, v32
	v_add_u32_e32 v18, s54, v33
	s_waitcnt lgkmcnt(0)
	v_and_b32_e32 v17, 0x7ff, v18
	v_ashrrev_i32_e32 v18, 11, v18
	v_add3_u32 v18, v18, s35, v17
	v_lshlrev_b32_e32 v34, 16, v10
	v_and_b32_e32 v35, 0xffff0000, v10
	v_lshlrev_b32_e32 v36, 16, v11
	v_and_b32_e32 v37, 0xffff0000, v11
	v_mov_b32_e32 v10, v15
	v_mov_b32_e32 v11, v16
	v_ashrrev_i32_e32 v19, 31, v18
	v_and_b32_e32 v41, 0xffff0000, v13
	v_lshlrev_b64 v[18:19], 12, v[18:19]
	v_lshlrev_b32_e32 v38, 16, v12
	v_and_b32_e32 v39, 0xffff0000, v12
	v_lshlrev_b32_e32 v40, 16, v13
	v_or_b32_e32 v18, v18, v1
	v_lshl_add_u64 v[12:13], s[62:63], 0, v[20:21]
	v_lshl_add_u64 v[20:21], s[64:65], 0, v[18:19]
	v_lshl_add_u64 v[16:17], s[0:1], 0, v[18:19]
	s_waitcnt vmcnt(11)
; #define GAS __attribute__((address_space(1)))
; #define LAS __attribute__((address_space(3)))
; __device__ __forceinline__ void unpack8(const v4u w, float (&f)[8]) { f[0] = bfl(w.x); f[1] = bfh(w.x); f[2] = bfl(w.y); f[3] = bfh(w.y); f[4] = bfl(w.z); f[5] = bfh(w.z); f[6] = bfl(w.w); f[7] = bfh(w.w); }
; __device__ __forceinline__ v4u pack8(const float (&f)[8]) { v4u w; w.x = pk2(f[0], f[1]); w.y = pk2(f[2], f[3]); w.z = pk2(f[4], f[5]); w.w = pk2(f[6], f[7]); return w; }
; template <bool COMBINE>
; __device__ __forceinline__ void attn_phase(Frame& F, const bf16* QKV, bf16* O12, float* LSE, bf16* MO) {
;     ...
;         for (int i = 0; i < 8; ++i) { const int ci = i * 64 + lane, row = ci >> 4, ch = ci & 15;
;             const v4u t = *(const LAS v4u*)(stg + row * SROW + ch * 16);
;             const size_t go = (size_t)tokrow(b, qw0 + row, Lsh) * D + h * 128 + ch * 8;
;             if (!COMBINE) *(GAS v4u*)(O12 + (size_t)(gg - 1) * M * D + go) = t;
;             else { const f32x4 wt = *(const LAS f32x4*)(stg + 32 * SROW + row * 16);
;                 const v4u a = *(const GAS v4u*)(O12 + go), bq = *(const GAS v4u*)(O12 + (size_t)M * D + go);
;                 float f0[8], f1[8], f2[8], r[8]; unpack8(t, f0); unpack8(a, f1); unpack8(bq, f2);
; #pragma unroll
;                 for (int jj = 0; jj < 8; ++jj) r[jj] = wt[0] * f0[jj] + wt[1] * f1[jj] + wt[2] * f2[jj];
;                 *(GAS v4u*)(MO + go) = pack8(r); }
	v_mov_b32_e32 v2, v88
	v_mov_b32_e32 v3, v89
	v_mov_b32_e32 v4, v90
	v_mov_b32_e32 v5, v91
	v_mov_b32_e32 v6, v92
	v_mov_b32_e32 v7, v93
	v_mov_b32_e32 v8, v94
	v_mov_b32_e32 v9, v95
	v_lshlrev_b32_e32 v23, 16, v2
	v_and_b32_e32 v25, 0xffff0000, v2
	v_lshlrev_b32_e32 v27, 16, v3
	v_lshlrev_b32_e32 v26, 16, v7
	v_and_b32_e32 v3, 0xffff0000, v3
	v_and_b32_e32 v2, 0xffff0000, v7
	v_lshlrev_b32_e32 v7, 16, v4
	v_and_b32_e32 v29, 0xffff0000, v4
	v_lshlrev_b32_e32 v31, 16, v5
	v_and_b32_e32 v5, 0xffff0000, v5
	v_and_b32_e32 v4, 0xffff0000, v9
	v_lshlrev_b32_e32 v22, 16, v6
	v_and_b32_e32 v24, 0xffff0000, v6
	v_lshlrev_b32_e32 v6, 16, v8
	v_and_b32_e32 v28, 0xffff0000, v8
	v_lshlrev_b32_e32 v30, 16, v9
	v_pk_mul_f32 v[2:3], v[10:11], v[2:3]
	v_pk_mul_f32 v[4:5], v[10:11], v[4:5]
	v_pk_mul_f32 v[8:9], v[10:11], v[22:23]
	v_pk_mul_f32 v[22:23], v[10:11], v[24:25]
	v_pk_mul_f32 v[24:25], v[10:11], v[26:27]
	v_pk_mul_f32 v[6:7], v[10:11], v[6:7]
	v_pk_mul_f32 v[26:27], v[10:11], v[28:29]
	v_pk_mul_f32 v[28:29], v[10:11], v[30:31]
	v_fma_f32 v2, v14, v37, v2
	v_fma_f32 v4, v14, v41, v4
	v_fma_f32 v8, v14, v34, v8
	v_fma_f32 v10, v14, v35, v22
	v_fma_f32 v11, v14, v36, v24
	v_fma_f32 v6, v14, v38, v6
	v_fma_f32 v15, v14, v39, v26
	v_fma_f32 v22, v14, v40, v28
	v_add_f32_e32 v3, v2, v3
	v_add_f32_e32 v5, v4, v5
	v_add_f32_e32 v8, v8, v9
	v_add_f32_e32 v9, v10, v23
	v_add_f32_e32 v10, v11, v25
	v_add_f32_e32 v6, v6, v7
	v_add_f32_e32 v7, v15, v27
	v_add_f32_e32 v11, v22, v29
	v_cvt_pk_bf16_f32 v2, v8, v9
	v_cvt_pk_bf16_f32 v3, v10, v3
	v_cvt_pk_bf16_f32 v4, v6, v7
	v_cvt_pk_bf16_f32 v5, v11, v5
	global_store_dwordx4 v[12:13], v[2:5], off
	v_and_b32_e32 v12, -16, v32
	v_mad_u64_u32 v[10:11], s[4:5], v33, s59, v[0:1]
	v_add_u32_e32 v14, s77, v12
	ds_read_b128 v[10:13], v10
	ds_read_b128 v[14:17], v14 offset:8704
	v_add_u32_e32 v34, 0x140, v198
	v_ashrrev_i32_e32 v32, 4, v34
	v_add_u32_e32 v20, s54, v32
	s_waitcnt lgkmcnt(0)
	v_and_b32_e32 v17, 0x7ff, v20
	v_ashrrev_i32_e32 v20, 11, v20
	v_add3_u32 v20, v20, s35, v17
	v_lshlrev_b32_e32 v33, 16, v10
	v_and_b32_e32 v35, 0xffff0000, v10
	v_lshlrev_b32_e32 v36, 16, v11
	v_and_b32_e32 v37, 0xffff0000, v11
	v_mov_b32_e32 v10, v15
	v_mov_b32_e32 v11, v16
	v_ashrrev_i32_e32 v21, 31, v20
	v_and_b32_e32 v41, 0xffff0000, v13
	v_lshlrev_b64 v[20:21], 12, v[20:21]
	v_lshlrev_b32_e32 v38, 16, v12
	v_and_b32_e32 v39, 0xffff0000, v12
	v_lshlrev_b32_e32 v40, 16, v13
	v_or_b32_e32 v20, v20, v1
	v_lshl_add_u64 v[12:13], s[62:63], 0, v[18:19]
	v_lshl_add_u64 v[18:19], s[64:65], 0, v[20:21]
	v_lshl_add_u64 v[16:17], s[0:1], 0, v[20:21]
	s_waitcnt vmcnt(10)
	v_mov_b32_e32 v2, v96
	v_mov_b32_e32 v3, v97
	v_mov_b32_e32 v4, v98
	v_mov_b32_e32 v5, v99
	v_mov_b32_e32 v6, v100
	v_mov_b32_e32 v7, v101
	v_mov_b32_e32 v8, v102
	v_mov_b32_e32 v9, v103
	v_lshlrev_b32_e32 v23, 16, v2
	v_and_b32_e32 v25, 0xffff0000, v2
	v_lshlrev_b32_e32 v27, 16, v3
	v_lshlrev_b32_e32 v26, 16, v7
	v_and_b32_e32 v3, 0xffff0000, v3
	v_and_b32_e32 v2, 0xffff0000, v7
	v_lshlrev_b32_e32 v7, 16, v4
	v_and_b32_e32 v29, 0xffff0000, v4
	v_lshlrev_b32_e32 v31, 16, v5
	v_and_b32_e32 v5, 0xffff0000, v5
	v_and_b32_e32 v4, 0xffff0000, v9
	v_lshlrev_b32_e32 v22, 16, v6
	v_and_b32_e32 v24, 0xffff0000, v6
	v_lshlrev_b32_e32 v6, 16, v8
	v_and_b32_e32 v28, 0xffff0000, v8
	v_lshlrev_b32_e32 v30, 16, v9
	v_pk_mul_f32 v[2:3], v[10:11], v[2:3]
	v_pk_mul_f32 v[4:5], v[10:11], v[4:5]
	v_pk_mul_f32 v[8:9], v[10:11], v[22:23]
	v_pk_mul_f32 v[22:23], v[10:11], v[24:25]
	v_pk_mul_f32 v[24:25], v[10:11], v[26:27]
	v_pk_mul_f32 v[6:7], v[10:11], v[6:7]
	v_pk_mul_f32 v[26:27], v[10:11], v[28:29]
	v_pk_mul_f32 v[28:29], v[10:11], v[30:31]
	v_fma_f32 v2, v14, v37, v2
	v_fma_f32 v4, v14, v41, v4
	v_fma_f32 v8, v14, v33, v8
	v_fma_f32 v10, v14, v35, v22
	v_fma_f32 v11, v14, v36, v24
	v_fma_f32 v6, v14, v38, v6
	v_fma_f32 v15, v14, v39, v26
	v_fma_f32 v22, v14, v40, v28
	v_add_f32_e32 v3, v2, v3
	v_add_f32_e32 v5, v4, v5
	v_add_f32_e32 v8, v8, v9
	v_add_f32_e32 v9, v10, v23
	v_add_f32_e32 v10, v11, v25
	v_add_f32_e32 v6, v6, v7
	v_add_f32_e32 v7, v15, v27
	v_add_f32_e32 v11, v22, v29
	v_cvt_pk_bf16_f32 v2, v8, v9
	v_cvt_pk_bf16_f32 v3, v10, v3
	v_cvt_pk_bf16_f32 v4, v6, v7
	v_cvt_pk_bf16_f32 v5, v11, v5
	global_store_dwordx4 v[12:13], v[2:5], off
	v_and_b32_e32 v12, -16, v34
	v_mad_u64_u32 v[10:11], s[4:5], v32, s59, v[0:1]
	v_add_u32_e32 v14, s77, v12
	ds_read_b128 v[10:13], v10
	ds_read_b128 v[14:17], v14 offset:8704
	v_add_u32_e32 v33, 0x180, v198
	v_ashrrev_i32_e32 v34, 4, v33
	v_add_u32_e32 v18, s54, v34
	s_waitcnt lgkmcnt(0)
	v_and_b32_e32 v17, 0x7ff, v18
	v_ashrrev_i32_e32 v18, 11, v18
	v_add3_u32 v18, v18, s35, v17
	v_lshlrev_b32_e32 v32, 16, v10
	v_and_b32_e32 v35, 0xffff0000, v10
	v_lshlrev_b32_e32 v36, 16, v11
	v_and_b32_e32 v37, 0xffff0000, v11
	v_mov_b32_e32 v10, v15
	v_mov_b32_e32 v11, v16
	v_ashrrev_i32_e32 v19, 31, v18
	v_and_b32_e32 v41, 0xffff0000, v13
	v_lshlrev_b64 v[18:19], 12, v[18:19]
	v_lshlrev_b32_e32 v38, 16, v12
	v_and_b32_e32 v39, 0xffff0000, v12
	v_lshlrev_b32_e32 v40, 16, v13
	v_or_b32_e32 v18, v18, v1
	v_lshl_add_u64 v[12:13], s[62:63], 0, v[20:21]
	v_lshl_add_u64 v[20:21], s[64:65], 0, v[18:19]
	v_lshl_add_u64 v[16:17], s[0:1], 0, v[18:19]
	s_waitcnt vmcnt(9)
; #define GAS __attribute__((address_space(1)))
; #define LAS __attribute__((address_space(3)))
; __device__ __forceinline__ void unpack8(const v4u w, float (&f)[8]) { f[0] = bfl(w.x); f[1] = bfh(w.x); f[2] = bfl(w.y); f[3] = bfh(w.y); f[4] = bfl(w.z); f[5] = bfh(w.z); f[6] = bfl(w.w); f[7] = bfh(w.w); }
; __device__ __forceinline__ v4u pack8(const float (&f)[8]) { v4u w; w.x = pk2(f[0], f[1]); w.y = pk2(f[2], f[3]); w.z = pk2(f[4], f[5]); w.w = pk2(f[6], f[7]); return w; }
; template <bool COMBINE>
; __device__ __forceinline__ void attn_phase(Frame& F, const bf16* QKV, bf16* O12, float* LSE, bf16* MO) {
;     ...
;         for (int i = 0; i < 8; ++i) { const int ci = i * 64 + lane, row = ci >> 4, ch = ci & 15;
;             const v4u t = *(const LAS v4u*)(stg + row * SROW + ch * 16);
;             const size_t go = (size_t)tokrow(b, qw0 + row, Lsh) * D + h * 128 + ch * 8;
;             if (!COMBINE) *(GAS v4u*)(O12 + (size_t)(gg - 1) * M * D + go) = t;
;             else { const f32x4 wt = *(const LAS f32x4*)(stg + 32 * SROW + row * 16);
;                 const v4u a = *(const GAS v4u*)(O12 + go), bq = *(const GAS v4u*)(O12 + (size_t)M * D + go);
;                 float f0[8], f1[8], f2[8], r[8]; unpack8(t, f0); unpack8(a, f1); unpack8(bq, f2);
; #pragma unroll
;                 for (int jj = 0; jj < 8; ++jj) r[jj] = wt[0] * f0[jj] + wt[1] * f1[jj] + wt[2] * f2[jj];
;                 *(GAS v4u*)(MO + go) = pack8(r); }
;         }
	v_mov_b32_e32 v2, v104
	v_mov_b32_e32 v3, v105
	v_mov_b32_e32 v4, v106
	v_mov_b32_e32 v5, v107
	v_mov_b32_e32 v6, v108
	v_mov_b32_e32 v7, v109
	v_mov_b32_e32 v8, v110
	v_mov_b32_e32 v9, v111
	v_lshlrev_b32_e32 v23, 16, v2
	v_and_b32_e32 v25, 0xffff0000, v2
	v_lshlrev_b32_e32 v27, 16, v3
	v_lshlrev_b32_e32 v26, 16, v7
	v_and_b32_e32 v3, 0xffff0000, v3
	v_and_b32_e32 v2, 0xffff0000, v7
	v_lshlrev_b32_e32 v7, 16, v4
	v_and_b32_e32 v29, 0xffff0000, v4
	v_lshlrev_b32_e32 v31, 16, v5
	v_and_b32_e32 v5, 0xffff0000, v5
	v_and_b32_e32 v4, 0xffff0000, v9
	v_lshlrev_b32_e32 v22, 16, v6
	v_and_b32_e32 v24, 0xffff0000, v6
	v_lshlrev_b32_e32 v6, 16, v8
	v_and_b32_e32 v28, 0xffff0000, v8
	v_lshlrev_b32_e32 v30, 16, v9
	v_pk_mul_f32 v[2:3], v[10:11], v[2:3]
	v_pk_mul_f32 v[4:5], v[10:11], v[4:5]
	v_pk_mul_f32 v[8:9], v[10:11], v[22:23]
	v_pk_mul_f32 v[22:23], v[10:11], v[24:25]
	v_pk_mul_f32 v[24:25], v[10:11], v[26:27]
	v_pk_mul_f32 v[6:7], v[10:11], v[6:7]
	v_pk_mul_f32 v[26:27], v[10:11], v[28:29]
	v_pk_mul_f32 v[28:29], v[10:11], v[30:31]
	v_fma_f32 v2, v14, v37, v2
	v_fma_f32 v4, v14, v41, v4
	v_fma_f32 v8, v14, v32, v8
	v_fma_f32 v10, v14, v35, v22
	v_fma_f32 v11, v14, v36, v24
	v_fma_f32 v6, v14, v38, v6
	v_fma_f32 v15, v14, v39, v26
	v_fma_f32 v22, v14, v40, v28
	v_add_f32_e32 v3, v2, v3
	v_add_f32_e32 v5, v4, v5
	v_add_f32_e32 v8, v8, v9
	v_add_f32_e32 v9, v10, v23
	v_add_f32_e32 v10, v11, v25
	v_add_f32_e32 v6, v6, v7
	v_add_f32_e32 v7, v15, v27
	v_add_f32_e32 v11, v22, v29
	v_cvt_pk_bf16_f32 v2, v8, v9
	v_cvt_pk_bf16_f32 v3, v10, v3
	v_cvt_pk_bf16_f32 v4, v6, v7
	v_cvt_pk_bf16_f32 v5, v11, v5
	global_store_dwordx4 v[12:13], v[2:5], off
	v_add_u32_e32 v32, 0x1c0, v198
	v_and_b32_e32 v12, -16, v33
	v_ashrrev_i32_e32 v33, 4, v32
	v_mad_u64_u32 v[10:11], s[4:5], v34, s59, v[0:1]
	v_add_u32_e32 v14, s77, v12
	v_add_u32_e32 v20, s54, v33
	ds_read_b128 v[10:13], v10
	ds_read_b128 v[14:17], v14 offset:8704
	s_waitcnt lgkmcnt(0)
	v_and_b32_e32 v17, 0x7ff, v20
	v_ashrrev_i32_e32 v20, 11, v20
	v_add3_u32 v20, v20, s35, v17
	v_ashrrev_i32_e32 v21, 31, v20
	v_lshlrev_b64 v[20:21], 12, v[20:21]
	v_or_b32_e32 v20, v20, v1
	v_lshlrev_b32_e32 v1, 16, v10
	v_and_b32_e32 v34, 0xffff0000, v10
	v_lshlrev_b32_e32 v35, 16, v11
	v_and_b32_e32 v36, 0xffff0000, v11
	v_mov_b32_e32 v10, v15
	v_mov_b32_e32 v11, v16
	v_and_b32_e32 v40, 0xffff0000, v13
	v_lshlrev_b32_e32 v37, 16, v12
	v_and_b32_e32 v38, 0xffff0000, v12
	v_lshlrev_b32_e32 v39, 16, v13
	v_lshl_add_u64 v[12:13], s[62:63], 0, v[18:19]
	v_lshl_add_u64 v[18:19], s[64:65], 0, v[20:21]
	v_lshl_add_u64 v[16:17], s[0:1], 0, v[20:21]
	s_waitcnt vmcnt(8)
	v_mov_b32_e32 v2, v112
	v_mov_b32_e32 v3, v113
	v_mov_b32_e32 v4, v114
	v_mov_b32_e32 v5, v115
	v_mov_b32_e32 v6, v116
	v_mov_b32_e32 v7, v117
	v_mov_b32_e32 v8, v118
	v_mov_b32_e32 v9, v119
	v_lshlrev_b32_e32 v23, 16, v2
	v_and_b32_e32 v25, 0xffff0000, v2
	v_lshlrev_b32_e32 v27, 16, v3
	v_lshlrev_b32_e32 v26, 16, v7
	v_and_b32_e32 v3, 0xffff0000, v3
	v_and_b32_e32 v2, 0xffff0000, v7
	v_lshlrev_b32_e32 v7, 16, v4
	v_and_b32_e32 v29, 0xffff0000, v4
	v_lshlrev_b32_e32 v31, 16, v5
	v_and_b32_e32 v5, 0xffff0000, v5
	v_and_b32_e32 v4, 0xffff0000, v9
	v_lshlrev_b32_e32 v22, 16, v6
	v_and_b32_e32 v24, 0xffff0000, v6
	v_lshlrev_b32_e32 v6, 16, v8
	v_and_b32_e32 v28, 0xffff0000, v8
	v_lshlrev_b32_e32 v30, 16, v9
	v_pk_mul_f32 v[2:3], v[10:11], v[2:3]
	v_pk_mul_f32 v[4:5], v[10:11], v[4:5]
	v_pk_mul_f32 v[8:9], v[10:11], v[22:23]
	v_pk_mul_f32 v[22:23], v[10:11], v[24:25]
	v_pk_mul_f32 v[24:25], v[10:11], v[26:27]
	v_pk_mul_f32 v[6:7], v[10:11], v[6:7]
	v_pk_mul_f32 v[26:27], v[10:11], v[28:29]
	v_pk_mul_f32 v[28:29], v[10:11], v[30:31]
	v_fma_f32 v2, v14, v36, v2
	v_fma_f32 v4, v14, v40, v4
	v_fma_f32 v1, v14, v1, v8
	v_fma_f32 v8, v14, v34, v22
	v_fma_f32 v10, v14, v35, v24
	v_fma_f32 v6, v14, v37, v6
	v_fma_f32 v11, v14, v38, v26
	v_fma_f32 v15, v14, v39, v28
	v_add_f32_e32 v3, v2, v3
	v_add_f32_e32 v5, v4, v5
	v_add_f32_e32 v1, v1, v9
	v_add_f32_e32 v8, v8, v23
	v_add_f32_e32 v9, v10, v25
	v_add_f32_e32 v6, v6, v7
	v_add_f32_e32 v7, v11, v27
	v_add_f32_e32 v10, v15, v29
	v_cvt_pk_bf16_f32 v2, v1, v8
	v_cvt_pk_bf16_f32 v3, v9, v3
	v_cvt_pk_bf16_f32 v4, v6, v7
	v_cvt_pk_bf16_f32 v5, v10, v5
	global_store_dwordx4 v[12:13], v[2:5], off
	v_mad_u64_u32 v[0:1], s[4:5], v33, s59, v[0:1]
	ds_read_b128 v[10:13], v0
	v_and_b32_e32 v0, -16, v32
	v_add_u32_e32 v0, s77, v0
	ds_read_b128 v[14:17], v0 offset:8704
	s_waitcnt lgkmcnt(1)
	v_lshlrev_b32_e32 v28, 16, v12
	v_and_b32_e32 v29, 0xffff0000, v12
	v_lshlrev_b32_e32 v30, 16, v13
	v_and_b32_e32 v31, 0xffff0000, v13
	s_waitcnt lgkmcnt(0)
	v_mov_b32_e32 v0, v15
	v_mov_b32_e32 v1, v16
	v_lshlrev_b32_e32 v24, 16, v10
	v_and_b32_e32 v25, 0xffff0000, v10
	v_lshlrev_b32_e32 v26, 16, v11
	v_and_b32_e32 v27, 0xffff0000, v11
	v_lshl_add_u64 v[10:11], s[62:63], 0, v[20:21]
	s_waitcnt vmcnt(7)
	v_mov_b32_e32 v2, v120
	v_mov_b32_e32 v3, v121
	v_mov_b32_e32 v4, v122
	v_mov_b32_e32 v5, v123
	v_mov_b32_e32 v6, v124
	v_mov_b32_e32 v7, v125
	v_mov_b32_e32 v8, v126
	v_mov_b32_e32 v9, v127
	v_lshlrev_b32_e32 v13, 16, v2
	v_lshlrev_b32_e32 v12, 16, v6
	v_and_b32_e32 v17, 0xffff0000, v2
	v_and_b32_e32 v16, 0xffff0000, v6
	v_lshlrev_b32_e32 v19, 16, v3
	v_lshlrev_b32_e32 v18, 16, v7
	v_and_b32_e32 v3, 0xffff0000, v3
	v_and_b32_e32 v2, 0xffff0000, v7
	v_lshlrev_b32_e32 v7, 16, v4
	v_lshlrev_b32_e32 v6, 16, v8
	v_and_b32_e32 v21, 0xffff0000, v4
	v_and_b32_e32 v20, 0xffff0000, v8
	v_lshlrev_b32_e32 v23, 16, v5
	v_lshlrev_b32_e32 v22, 16, v9
	v_and_b32_e32 v5, 0xffff0000, v5
	v_and_b32_e32 v4, 0xffff0000, v9
	v_pk_mul_f32 v[2:3], v[0:1], v[2:3]
	v_pk_mul_f32 v[6:7], v[0:1], v[6:7]
	v_pk_mul_f32 v[8:9], v[0:1], v[12:13]
	v_pk_mul_f32 v[12:13], v[0:1], v[16:17]
	v_pk_mul_f32 v[16:17], v[0:1], v[18:19]
	v_pk_mul_f32 v[18:19], v[0:1], v[20:21]
	v_pk_mul_f32 v[20:21], v[0:1], v[22:23]
	v_pk_mul_f32 v[0:1], v[0:1], v[4:5]
	v_fma_f32 v2, v14, v27, v2
	v_fma_f32 v6, v14, v28, v6
	v_fma_f32 v4, v14, v24, v8
	v_fma_f32 v5, v14, v25, v12
	v_fma_f32 v8, v14, v26, v16
	v_fma_f32 v12, v14, v29, v18
	v_fma_f32 v15, v14, v30, v20
	v_fma_f32 v0, v14, v31, v0
	v_add_f32_e32 v2, v2, v3
	v_add_f32_e32 v3, v6, v7
	v_add_f32_e32 v4, v4, v9
	v_add_f32_e32 v5, v5, v13
	v_add_f32_e32 v8, v8, v17
	v_add_f32_e32 v6, v12, v19
	v_add_f32_e32 v7, v15, v21
	v_add_f32_e32 v9, v0, v1
	v_cvt_pk_bf16_f32 v0, v4, v5
	v_cvt_pk_bf16_f32 v1, v8, v2
	v_cvt_pk_bf16_f32 v2, v3, v6
	v_cvt_pk_bf16_f32 v3, v7, v9
	global_store_dwordx4 v[10:11], v[0:3], off
	s_cbranch_scc0 .LBB0_493
